# GEMM K-loops: first 4 MFMAs of each 32-MFMA segment issued before the opening barrier at priority 0 (they only read registers), so the load-role wave fills matrix-pipe gaps while its partner finishes;
# baseline (speedup 1.0000x reference)
.LBB0_320:
	s_add_u32 s20, s40, 0xfffc0080
	s_addc_u32 s21, s41, -1
	s_add_i32 s77, 0, 0x10000
	s_cmp_eq_u32 s76, 12
	s_cselect_b32 s59, s49, s21
	s_cselect_b32 s58, s55, s20
	s_cselect_b32 s21, s45, s75
	s_cselect_b32 s20, s73, s74
	s_add_i32 s80, 0, 0x14000
	v_add_u32_e32 v60, s77, v183
	v_add_u32_e32 v168, s80, v183
	ds_read_b128 v[48:51], v60
	ds_read_b128 v[52:55], v60 offset:1024
	ds_read_b128 v[56:59], v60 offset:2048
	ds_read_b128 v[60:63], v60 offset:3072
	ds_read_b128 v[164:167], v168
	ds_read_b128 v[170:173], v168 offset:1024
	ds_read_b128 v[174:177], v168 offset:2048
	ds_read_b128 v[178:181], v168 offset:3072
	v_lshl_add_u64 v[228:229], s[40:41], 0, v[162:163]
	s_add_i32 m0, s57, 0xc000
	ds_read_b128 v[204:207], v202
	ds_read_b128 v[208:211], v202 offset:1024
	ds_read_b128 v[212:215], v202 offset:2048
	ds_read_b128 v[216:219], v202 offset:3072
	ds_read_b128 v[220:223], v202 offset:4096
	ds_read_b128 v[224:227], v202 offset:5120
	ds_read_b128 v[240:243], v202 offset:6144
	ds_read_b128 v[244:247], v202 offset:7168
	global_load_lds_dwordx4 v[228:229], off
	v_lshl_add_u64 v[228:229], s[40:41], 0, v[160:161]
	s_add_i32 m0, s57, 0xe000
	s_nop 0
	global_load_lds_dwordx4 v[228:229], off
	s_waitcnt vmcnt(8)
	s_waitcnt lgkmcnt(0)
	v_mfma_f32_16x16x32_bf16 v[140:143], v[48:51], v[204:207], v[140:143]
	v_mfma_f32_16x16x32_bf16 v[140:143], v[52:55], v[208:211], v[140:143]
	v_mfma_f32_16x16x32_bf16 v[136:139], v[56:59], v[204:207], v[136:139]
	v_mfma_f32_16x16x32_bf16 v[136:139], v[60:63], v[208:211], v[136:139]
	s_setprio 1
	s_barrier
	v_mfma_f32_16x16x32_bf16 v[124:127], v[48:51], v[212:215], v[124:127]
	v_mfma_f32_16x16x32_bf16 v[124:127], v[52:55], v[216:219], v[124:127]
	v_mfma_f32_16x16x32_bf16 v[120:123], v[56:59], v[212:215], v[120:123]
	v_mfma_f32_16x16x32_bf16 v[120:123], v[60:63], v[216:219], v[120:123]
	v_mfma_f32_16x16x32_bf16 v[108:111], v[48:51], v[220:223], v[108:111]
	v_mfma_f32_16x16x32_bf16 v[108:111], v[52:55], v[224:227], v[108:111]
	v_mfma_f32_16x16x32_bf16 v[104:107], v[56:59], v[220:223], v[104:107]
	v_mfma_f32_16x16x32_bf16 v[104:107], v[60:63], v[224:227], v[104:107]
	v_mfma_f32_16x16x32_bf16 v[92:95], v[48:51], v[240:243], v[92:95]
	v_mfma_f32_16x16x32_bf16 v[92:95], v[52:55], v[244:247], v[92:95]
	v_mfma_f32_16x16x32_bf16 v[88:91], v[56:59], v[240:243], v[88:91]
	v_mfma_f32_16x16x32_bf16 v[88:91], v[60:63], v[244:247], v[88:91]
	v_mfma_f32_16x16x32_bf16 v[132:135], v[164:167], v[204:207], v[132:135]
	v_mfma_f32_16x16x32_bf16 v[132:135], v[170:173], v[208:211], v[132:135]
	v_mfma_f32_16x16x32_bf16 v[128:131], v[174:177], v[204:207], v[128:131]
	v_mfma_f32_16x16x32_bf16 v[128:131], v[178:181], v[208:211], v[128:131]
	v_mfma_f32_16x16x32_bf16 v[116:119], v[164:167], v[212:215], v[116:119]
	v_mfma_f32_16x16x32_bf16 v[116:119], v[170:173], v[216:219], v[116:119]
	v_mfma_f32_16x16x32_bf16 v[112:115], v[174:177], v[212:215], v[112:115]
	v_mfma_f32_16x16x32_bf16 v[112:115], v[178:181], v[216:219], v[112:115]
	v_mfma_f32_16x16x32_bf16 v[100:103], v[164:167], v[220:223], v[100:103]
	v_mfma_f32_16x16x32_bf16 v[100:103], v[170:173], v[224:227], v[100:103]
	v_mfma_f32_16x16x32_bf16 v[96:99], v[174:177], v[220:223], v[96:99]
	v_mfma_f32_16x16x32_bf16 v[96:99], v[178:181], v[224:227], v[96:99]
	v_mfma_f32_16x16x32_bf16 v[84:87], v[164:167], v[240:243], v[84:87]
	v_mfma_f32_16x16x32_bf16 v[84:87], v[170:173], v[244:247], v[84:87]
	v_mfma_f32_16x16x32_bf16 v[80:83], v[174:177], v[240:243], v[80:83]
	v_mfma_f32_16x16x32_bf16 v[80:83], v[178:181], v[244:247], v[80:83]
	s_barrier
	s_setprio 0
	s_add_i32 s77, s77, s62
	v_lshl_add_u64 v[228:229], s[20:21], 0, v[146:147]
	s_mov_b32 m0, s77
	ds_read_b128 v[204:207], v202 offset:16384
	ds_read_b128 v[208:211], v202 offset:17408
	ds_read_b128 v[212:215], v202 offset:18432
	ds_read_b128 v[216:219], v202 offset:19456
	ds_read_b128 v[220:223], v202 offset:20480
	ds_read_b128 v[224:227], v202 offset:21504
	ds_read_b128 v[240:243], v202 offset:22528
	ds_read_b128 v[244:247], v202 offset:23552
	global_load_lds_dwordx4 v[228:229], off
	s_add_i32 m0, s77, 0x2000
	s_add_u32 s78, s20, 0x40000
	v_lshl_add_u64 v[230:231], s[20:21], 0, v[150:151]
	s_addc_u32 s79, s21, 0
	s_add_i32 s77, s80, s62
	global_load_lds_dwordx4 v[230:231], off
	v_lshl_add_u64 v[232:233], s[78:79], 0, v[146:147]
	s_mov_b32 m0, s77
	v_lshl_add_u64 v[234:235], s[58:59], 0, v[148:149]
	global_load_lds_dwordx4 v[232:233], off
	v_lshl_add_u64 v[232:233], s[78:79], 0, v[150:151]
	s_add_i32 m0, s77, 0x2000
	s_nop 0
	global_load_lds_dwordx4 v[232:233], off
	v_lshl_add_u64 v[232:233], s[58:59], 0, v[144:145]
	s_mov_b32 m0, s57
	s_nop 0
	global_load_lds_dwordx4 v[232:233], off
	s_mov_b32 m0, s65
	s_nop 0
	global_load_lds_dwordx4 v[234:235], off
	s_waitcnt vmcnt(8)
	s_waitcnt lgkmcnt(0)
	v_mfma_f32_16x16x32_bf16 v[76:79], v[48:51], v[204:207], v[76:79]
	v_mfma_f32_16x16x32_bf16 v[76:79], v[52:55], v[208:211], v[76:79]
	v_mfma_f32_16x16x32_bf16 v[72:75], v[56:59], v[204:207], v[72:75]
	v_mfma_f32_16x16x32_bf16 v[72:75], v[60:63], v[208:211], v[72:75]
	s_setprio 1
	s_barrier
	v_mfma_f32_16x16x32_bf16 v[44:47], v[48:51], v[212:215], v[44:47]
	v_mfma_f32_16x16x32_bf16 v[44:47], v[52:55], v[216:219], v[44:47]
	v_mfma_f32_16x16x32_bf16 v[40:43], v[56:59], v[212:215], v[40:43]
	v_mfma_f32_16x16x32_bf16 v[40:43], v[60:63], v[216:219], v[40:43]
	v_mfma_f32_16x16x32_bf16 v[28:31], v[48:51], v[220:223], v[28:31]
	v_mfma_f32_16x16x32_bf16 v[28:31], v[52:55], v[224:227], v[28:31]
	v_mfma_f32_16x16x32_bf16 v[24:27], v[56:59], v[220:223], v[24:27]
	v_mfma_f32_16x16x32_bf16 v[24:27], v[60:63], v[224:227], v[24:27]
	v_mfma_f32_16x16x32_bf16 v[12:15], v[48:51], v[240:243], v[12:15]
	v_mfma_f32_16x16x32_bf16 v[12:15], v[52:55], v[244:247], v[12:15]
	v_mfma_f32_16x16x32_bf16 v[8:11], v[56:59], v[240:243], v[8:11]
	v_mfma_f32_16x16x32_bf16 v[8:11], v[60:63], v[244:247], v[8:11]
	v_mfma_f32_16x16x32_bf16 v[36:39], v[164:167], v[212:215], v[36:39]
	v_mfma_f32_16x16x32_bf16 v[36:39], v[170:173], v[216:219], v[36:39]
	v_mfma_f32_16x16x32_bf16 v[32:35], v[174:177], v[212:215], v[32:35]
	v_mfma_f32_16x16x32_bf16 v[32:35], v[178:181], v[216:219], v[32:35]
	v_mfma_f32_16x16x32_bf16 v[20:23], v[164:167], v[220:223], v[20:23]
	v_mfma_f32_16x16x32_bf16 v[20:23], v[170:173], v[224:227], v[20:23]
	v_mfma_f32_16x16x32_bf16 v[16:19], v[174:177], v[220:223], v[16:19]
	v_mfma_f32_16x16x32_bf16 v[16:19], v[178:181], v[224:227], v[16:19]
	v_mfma_f32_16x16x32_bf16 v[4:7], v[164:167], v[240:243], v[4:7]
	v_mfma_f32_16x16x32_bf16 v[4:7], v[170:173], v[244:247], v[4:7]
	v_mfma_f32_16x16x32_bf16 v[0:3], v[174:177], v[240:243], v[0:3]
	v_mfma_f32_16x16x32_bf16 v[0:3], v[178:181], v[244:247], v[0:3]
	v_mfma_f32_16x16x32_bf16 v[48:51], v[164:167], v[204:207], v[68:71]
	v_mfma_f32_16x16x32_bf16 v[48:51], v[170:173], v[208:211], v[48:51]
	v_mfma_f32_16x16x32_bf16 v[52:55], v[174:177], v[204:207], v[64:67]
	v_mfma_f32_16x16x32_bf16 v[52:55], v[178:181], v[208:211], v[52:55]
	s_barrier
	s_setprio 0
	s_add_i32 s77, 0, 0x18000
	s_add_i32 s78, 0, 0x1c000
	v_add_u32_e32 v68, s77, v183
	v_add_u32_e32 v168, s78, v183
	ds_read_b128 v[56:59], v68
	ds_read_b128 v[60:63], v68 offset:1024
	ds_read_b128 v[64:67], v68 offset:2048
	ds_read_b128 v[68:71], v68 offset:3072
	ds_read_b128 v[164:167], v168
	ds_read_b128 v[170:173], v168 offset:1024
	ds_read_b128 v[174:177], v168 offset:2048
	ds_read_b128 v[178:181], v168 offset:3072
	s_add_u32 s58, s58, 0x40000
	s_addc_u32 s59, s59, 0
	s_mov_b32 m0, s66
	v_lshl_add_u64 v[236:237], s[58:59], 0, v[144:145]
	ds_read_b128 v[204:207], v202 offset:32768
	ds_read_b128 v[208:211], v202 offset:33792
	ds_read_b128 v[212:215], v202 offset:34816
	ds_read_b128 v[216:219], v202 offset:35840
	ds_read_b128 v[220:223], v202 offset:36864
	ds_read_b128 v[224:227], v202 offset:37888
	ds_read_b128 v[240:243], v202 offset:38912
	ds_read_b128 v[244:247], v202 offset:39936
	global_load_lds_dwordx4 v[236:237], off
	v_lshl_add_u64 v[236:237], s[58:59], 0, v[148:149]
	s_mov_b32 m0, s67
	s_nop 0
	global_load_lds_dwordx4 v[236:237], off
	s_waitcnt vmcnt(8)
	s_waitcnt lgkmcnt(0)
	v_mfma_f32_16x16x32_bf16 v[140:143], v[56:59], v[204:207], v[140:143]
	v_mfma_f32_16x16x32_bf16 v[140:143], v[60:63], v[208:211], v[140:143]
	v_mfma_f32_16x16x32_bf16 v[136:139], v[64:67], v[204:207], v[136:139]
	v_mfma_f32_16x16x32_bf16 v[136:139], v[68:71], v[208:211], v[136:139]
	s_setprio 1
	s_barrier
	v_mfma_f32_16x16x32_bf16 v[124:127], v[56:59], v[212:215], v[124:127]
	v_mfma_f32_16x16x32_bf16 v[124:127], v[60:63], v[216:219], v[124:127]
	v_mfma_f32_16x16x32_bf16 v[120:123], v[64:67], v[212:215], v[120:123]
	v_mfma_f32_16x16x32_bf16 v[120:123], v[68:71], v[216:219], v[120:123]
	v_mfma_f32_16x16x32_bf16 v[108:111], v[56:59], v[220:223], v[108:111]
	v_mfma_f32_16x16x32_bf16 v[108:111], v[60:63], v[224:227], v[108:111]
	v_mfma_f32_16x16x32_bf16 v[104:107], v[64:67], v[220:223], v[104:107]
	v_mfma_f32_16x16x32_bf16 v[104:107], v[68:71], v[224:227], v[104:107]
	v_mfma_f32_16x16x32_bf16 v[92:95], v[56:59], v[240:243], v[92:95]
	v_mfma_f32_16x16x32_bf16 v[92:95], v[60:63], v[244:247], v[92:95]
	v_mfma_f32_16x16x32_bf16 v[88:91], v[64:67], v[240:243], v[88:91]
	v_mfma_f32_16x16x32_bf16 v[88:91], v[68:71], v[244:247], v[88:91]
	v_mfma_f32_16x16x32_bf16 v[132:135], v[164:167], v[204:207], v[132:135]
	v_mfma_f32_16x16x32_bf16 v[132:135], v[170:173], v[208:211], v[132:135]
	v_mfma_f32_16x16x32_bf16 v[128:131], v[174:177], v[204:207], v[128:131]
	v_mfma_f32_16x16x32_bf16 v[128:131], v[178:181], v[208:211], v[128:131]
	v_mfma_f32_16x16x32_bf16 v[116:119], v[164:167], v[212:215], v[116:119]
	v_mfma_f32_16x16x32_bf16 v[116:119], v[170:173], v[216:219], v[116:119]
	v_mfma_f32_16x16x32_bf16 v[112:115], v[174:177], v[212:215], v[112:115]
	v_mfma_f32_16x16x32_bf16 v[112:115], v[178:181], v[216:219], v[112:115]
	v_mfma_f32_16x16x32_bf16 v[100:103], v[164:167], v[220:223], v[100:103]
	v_mfma_f32_16x16x32_bf16 v[100:103], v[170:173], v[224:227], v[100:103]
	v_mfma_f32_16x16x32_bf16 v[96:99], v[174:177], v[220:223], v[96:99]
	v_mfma_f32_16x16x32_bf16 v[96:99], v[178:181], v[224:227], v[96:99]
	v_mfma_f32_16x16x32_bf16 v[84:87], v[164:167], v[240:243], v[84:87]
	v_mfma_f32_16x16x32_bf16 v[84:87], v[170:173], v[244:247], v[84:87]
	v_mfma_f32_16x16x32_bf16 v[80:83], v[174:177], v[240:243], v[80:83]
	v_mfma_f32_16x16x32_bf16 v[80:83], v[178:181], v[244:247], v[80:83]
	s_barrier
	s_setprio 0
	s_add_i32 s58, s77, s62
	v_lshl_add_u64 v[228:229], v[228:229], 0, s[36:37]
	s_mov_b32 m0, s58
	ds_read_b128 v[204:207], v202 offset:49152
	ds_read_b128 v[208:211], v202 offset:50176
	ds_read_b128 v[212:215], v202 offset:51200
	ds_read_b128 v[216:219], v202 offset:52224
	ds_read_b128 v[220:223], v202 offset:53248
	ds_read_b128 v[224:227], v202 offset:54272
	ds_read_b128 v[240:243], v202 offset:55296
	ds_read_b128 v[244:247], v202 offset:56320
	global_load_lds_dwordx4 v[228:229], off
	s_add_i32 m0, s58, 0x2000
	s_add_u32 s20, s20, 0x40080
	v_lshl_add_u64 v[228:229], v[230:231], 0, s[36:37]
	s_addc_u32 s21, s21, 0
	s_add_i32 s58, s78, s62
	global_load_lds_dwordx4 v[228:229], off
	v_lshl_add_u64 v[228:229], s[20:21], 0, v[146:147]
	s_mov_b32 m0, s58
	s_nop 0
	global_load_lds_dwordx4 v[228:229], off
	v_lshl_add_u64 v[228:229], s[20:21], 0, v[150:151]
	s_add_i32 m0, s58, 0x2000
	s_nop 0
	global_load_lds_dwordx4 v[228:229], off
	v_lshl_add_u64 v[228:229], v[232:233], 0, s[36:37]
	s_mov_b32 m0, s69
	s_nop 0
	global_load_lds_dwordx4 v[228:229], off
	v_lshl_add_u64 v[228:229], v[234:235], 0, s[36:37]
	s_mov_b32 m0, s70
	s_nop 0
	global_load_lds_dwordx4 v[228:229], off
	s_waitcnt vmcnt(8)
	s_waitcnt lgkmcnt(0)
	v_mfma_f32_16x16x32_bf16 v[76:79], v[56:59], v[204:207], v[76:79]
	v_mfma_f32_16x16x32_bf16 v[76:79], v[60:63], v[208:211], v[76:79]
	v_mfma_f32_16x16x32_bf16 v[72:75], v[64:67], v[204:207], v[72:75]
	v_mfma_f32_16x16x32_bf16 v[72:75], v[68:71], v[208:211], v[72:75]
	s_setprio 1
	s_barrier
	v_mfma_f32_16x16x32_bf16 v[44:47], v[56:59], v[212:215], v[44:47]
	v_mfma_f32_16x16x32_bf16 v[44:47], v[60:63], v[216:219], v[44:47]
	v_mfma_f32_16x16x32_bf16 v[40:43], v[64:67], v[212:215], v[40:43]
	v_mfma_f32_16x16x32_bf16 v[40:43], v[68:71], v[216:219], v[40:43]
	v_mfma_f32_16x16x32_bf16 v[28:31], v[56:59], v[220:223], v[28:31]
	v_mfma_f32_16x16x32_bf16 v[28:31], v[60:63], v[224:227], v[28:31]
	v_mfma_f32_16x16x32_bf16 v[24:27], v[64:67], v[220:223], v[24:27]
	v_mfma_f32_16x16x32_bf16 v[24:27], v[68:71], v[224:227], v[24:27]
	v_mfma_f32_16x16x32_bf16 v[12:15], v[56:59], v[240:243], v[12:15]
	v_mfma_f32_16x16x32_bf16 v[12:15], v[60:63], v[244:247], v[12:15]
	v_mfma_f32_16x16x32_bf16 v[8:11], v[64:67], v[240:243], v[8:11]
	v_mfma_f32_16x16x32_bf16 v[8:11], v[68:71], v[244:247], v[8:11]
	v_mfma_f32_16x16x32_bf16 v[48:51], v[164:167], v[204:207], v[48:51]
	v_mfma_f32_16x16x32_bf16 v[68:71], v[170:173], v[208:211], v[48:51]
	v_mfma_f32_16x16x32_bf16 v[48:51], v[174:177], v[204:207], v[52:55]
	v_mfma_f32_16x16x32_bf16 v[36:39], v[164:167], v[212:215], v[36:39]
	v_mfma_f32_16x16x32_bf16 v[32:35], v[174:177], v[212:215], v[32:35]
	v_mfma_f32_16x16x32_bf16 v[20:23], v[164:167], v[220:223], v[20:23]
	v_mfma_f32_16x16x32_bf16 v[16:19], v[174:177], v[220:223], v[16:19]
	v_mfma_f32_16x16x32_bf16 v[4:7], v[164:167], v[240:243], v[4:7]
	v_mfma_f32_16x16x32_bf16 v[0:3], v[174:177], v[240:243], v[0:3]
	v_mfma_f32_16x16x32_bf16 v[64:67], v[178:181], v[208:211], v[48:51]
	v_mfma_f32_16x16x32_bf16 v[36:39], v[170:173], v[216:219], v[36:39]
	v_mfma_f32_16x16x32_bf16 v[32:35], v[178:181], v[216:219], v[32:35]
	v_mfma_f32_16x16x32_bf16 v[20:23], v[170:173], v[224:227], v[20:23]
	v_mfma_f32_16x16x32_bf16 v[16:19], v[178:181], v[224:227], v[16:19]
	v_mfma_f32_16x16x32_bf16 v[4:7], v[170:173], v[244:247], v[4:7]
	v_mfma_f32_16x16x32_bf16 v[0:3], v[178:181], v[244:247], v[0:3]
	s_barrier
	s_setprio 0
	s_add_i32 s76, s76, 2
	s_add_u32 s74, s74, 0x100
	s_addc_u32 s75, s75, 0
	s_add_u32 s40, s40, 0x100
	s_addc_u32 s41, s41, 0
	s_cmp_gt_u32 s76, 13
	s_cbranch_scc0 .LBB0_320
	s_and_b64 vcc, exec, s[42:43]
	s_cbranch_vccz .LBB0_323
	s_barrier

.LBB0_478:
	s_add_u32 s20, s40, 0xfffc0080
	s_addc_u32 s21, s41, -1
	s_add_i32 s65, 0, 0x10000
	s_cmp_eq_u32 s64, 12
	s_cselect_b32 s43, s15, s21
	s_cselect_b32 s42, s45, s20
	v_add_u32_e32 v167, s65, v149
	s_cselect_b32 s21, s13, s63
	s_cselect_b32 s20, s61, s62
	s_add_i32 s68, 0, 0x14000
	ds_read_b128 v[140:143], v167
	ds_read_b128 v[144:147], v167 offset:1024
	ds_read_b128 v[170:173], v167 offset:2048
	ds_read_b128 v[174:177], v167 offset:3072
	v_add_u32_e32 v167, s68, v149
	ds_read_b128 v[178:181], v167
	ds_read_b128 v[182:185], v167 offset:1024
	ds_read_b128 v[186:189], v167 offset:2048
	ds_read_b128 v[190:193], v167 offset:3072
	v_lshl_add_u64 v[226:227], s[40:41], 0, v[138:139]
	s_add_i32 m0, s53, 0xc000
	ds_read_b128 v[194:197], v166
	ds_read_b128 v[198:201], v166 offset:1024
	ds_read_b128 v[202:205], v166 offset:2048
	ds_read_b128 v[206:209], v166 offset:3072
	ds_read_b128 v[210:213], v166 offset:4096
	ds_read_b128 v[214:217], v166 offset:5120
	ds_read_b128 v[218:221], v166 offset:6144
	ds_read_b128 v[222:225], v166 offset:7168
	global_load_lds_dwordx4 v[226:227], off
	v_lshl_add_u64 v[226:227], s[40:41], 0, v[136:137]
	s_add_i32 m0, s53, 0xe000
	s_nop 0
	global_load_lds_dwordx4 v[226:227], off
	s_waitcnt vmcnt(8)
	s_waitcnt lgkmcnt(0)
	v_mfma_f32_16x16x32_bf16 v[124:127], v[140:143], v[194:197], v[124:127]
	v_mfma_f32_16x16x32_bf16 v[124:127], v[144:147], v[198:201], v[124:127]
	v_mfma_f32_16x16x32_bf16 v[120:123], v[170:173], v[194:197], v[120:123]
	v_mfma_f32_16x16x32_bf16 v[120:123], v[174:177], v[198:201], v[120:123]
	s_setprio 1
	s_barrier
	v_mfma_f32_16x16x32_bf16 v[108:111], v[140:143], v[202:205], v[108:111]
	v_mfma_f32_16x16x32_bf16 v[108:111], v[144:147], v[206:209], v[108:111]
	v_mfma_f32_16x16x32_bf16 v[104:107], v[170:173], v[202:205], v[104:107]
	v_mfma_f32_16x16x32_bf16 v[104:107], v[174:177], v[206:209], v[104:107]
	v_mfma_f32_16x16x32_bf16 v[92:95], v[140:143], v[210:213], v[92:95]
	v_mfma_f32_16x16x32_bf16 v[92:95], v[144:147], v[214:217], v[92:95]
	v_mfma_f32_16x16x32_bf16 v[88:91], v[170:173], v[210:213], v[88:91]
	v_mfma_f32_16x16x32_bf16 v[88:91], v[174:177], v[214:217], v[88:91]
	v_mfma_f32_16x16x32_bf16 v[76:79], v[140:143], v[218:221], v[76:79]
	v_mfma_f32_16x16x32_bf16 v[76:79], v[144:147], v[222:225], v[76:79]
	v_mfma_f32_16x16x32_bf16 v[72:75], v[170:173], v[218:221], v[72:75]
	v_mfma_f32_16x16x32_bf16 v[72:75], v[174:177], v[222:225], v[72:75]
	v_mfma_f32_16x16x32_bf16 v[116:119], v[178:181], v[194:197], v[116:119]
	v_mfma_f32_16x16x32_bf16 v[116:119], v[182:185], v[198:201], v[116:119]
	v_mfma_f32_16x16x32_bf16 v[112:115], v[186:189], v[194:197], v[112:115]
	v_mfma_f32_16x16x32_bf16 v[112:115], v[190:193], v[198:201], v[112:115]
	v_mfma_f32_16x16x32_bf16 v[100:103], v[178:181], v[202:205], v[100:103]
	v_mfma_f32_16x16x32_bf16 v[100:103], v[182:185], v[206:209], v[100:103]
	v_mfma_f32_16x16x32_bf16 v[96:99], v[186:189], v[202:205], v[96:99]
	v_mfma_f32_16x16x32_bf16 v[96:99], v[190:193], v[206:209], v[96:99]
	v_mfma_f32_16x16x32_bf16 v[84:87], v[178:181], v[210:213], v[84:87]
	v_mfma_f32_16x16x32_bf16 v[84:87], v[182:185], v[214:217], v[84:87]
	v_mfma_f32_16x16x32_bf16 v[80:83], v[186:189], v[210:213], v[80:83]
	v_mfma_f32_16x16x32_bf16 v[80:83], v[190:193], v[214:217], v[80:83]
	v_mfma_f32_16x16x32_bf16 v[68:71], v[178:181], v[218:221], v[68:71]
	v_mfma_f32_16x16x32_bf16 v[68:71], v[182:185], v[222:225], v[68:71]
	v_mfma_f32_16x16x32_bf16 v[64:67], v[186:189], v[218:221], v[64:67]
	v_mfma_f32_16x16x32_bf16 v[64:67], v[190:193], v[222:225], v[64:67]
	s_barrier
	s_setprio 0
	s_add_i32 s65, s65, s50
	v_lshl_add_u64 v[226:227], s[20:21], 0, v[132:133]
	s_mov_b32 m0, s65
	ds_read_b128 v[194:197], v166 offset:16384
	ds_read_b128 v[198:201], v166 offset:17408
	ds_read_b128 v[202:205], v166 offset:18432
	ds_read_b128 v[206:209], v166 offset:19456
	ds_read_b128 v[210:213], v166 offset:20480
	ds_read_b128 v[214:217], v166 offset:21504
	ds_read_b128 v[218:221], v166 offset:22528
	ds_read_b128 v[222:225], v166 offset:23552
	global_load_lds_dwordx4 v[226:227], off
	s_add_i32 m0, s65, 0x2000
	s_add_u32 s66, s20, 0x40000
	v_lshl_add_u64 v[228:229], s[20:21], 0, v[128:129]
	s_addc_u32 s67, s21, 0
	s_add_i32 s65, s68, s50
	global_load_lds_dwordx4 v[228:229], off
	v_lshl_add_u64 v[230:231], s[66:67], 0, v[132:133]
	s_mov_b32 m0, s65
	v_lshl_add_u64 v[232:233], s[42:43], 0, v[130:131]
	global_load_lds_dwordx4 v[230:231], off
	v_lshl_add_u64 v[230:231], s[66:67], 0, v[128:129]
	s_add_i32 m0, s65, 0x2000
	s_nop 0
	global_load_lds_dwordx4 v[230:231], off
	v_lshl_add_u64 v[230:231], s[42:43], 0, v[134:135]
	s_mov_b32 m0, s53
	s_nop 0
	global_load_lds_dwordx4 v[230:231], off
	s_mov_b32 m0, s54
	s_nop 0
	global_load_lds_dwordx4 v[232:233], off
	s_waitcnt vmcnt(8)
	s_waitcnt lgkmcnt(0)
	v_mfma_f32_16x16x32_bf16 v[60:63], v[140:143], v[194:197], v[60:63]
	v_mfma_f32_16x16x32_bf16 v[60:63], v[144:147], v[198:201], v[60:63]
	v_mfma_f32_16x16x32_bf16 v[56:59], v[170:173], v[194:197], v[56:59]
	v_mfma_f32_16x16x32_bf16 v[56:59], v[174:177], v[198:201], v[56:59]
	s_setprio 1
	s_barrier
	v_mfma_f32_16x16x32_bf16 v[44:47], v[140:143], v[202:205], v[44:47]
	v_mfma_f32_16x16x32_bf16 v[44:47], v[144:147], v[206:209], v[44:47]
	v_mfma_f32_16x16x32_bf16 v[40:43], v[170:173], v[202:205], v[40:43]
	v_mfma_f32_16x16x32_bf16 v[40:43], v[174:177], v[206:209], v[40:43]
	v_mfma_f32_16x16x32_bf16 v[28:31], v[140:143], v[210:213], v[28:31]
	v_mfma_f32_16x16x32_bf16 v[28:31], v[144:147], v[214:217], v[28:31]
	v_mfma_f32_16x16x32_bf16 v[24:27], v[170:173], v[210:213], v[24:27]
	v_mfma_f32_16x16x32_bf16 v[24:27], v[174:177], v[214:217], v[24:27]
	v_mfma_f32_16x16x32_bf16 v[12:15], v[140:143], v[218:221], v[12:15]
	v_mfma_f32_16x16x32_bf16 v[12:15], v[144:147], v[222:225], v[12:15]
	v_mfma_f32_16x16x32_bf16 v[8:11], v[170:173], v[218:221], v[8:11]
	v_mfma_f32_16x16x32_bf16 v[8:11], v[174:177], v[222:225], v[8:11]
	v_mfma_f32_16x16x32_bf16 v[52:55], v[178:181], v[194:197], v[52:55]
	v_mfma_f32_16x16x32_bf16 v[52:55], v[182:185], v[198:201], v[52:55]
	v_mfma_f32_16x16x32_bf16 v[48:51], v[186:189], v[194:197], v[48:51]
	v_mfma_f32_16x16x32_bf16 v[48:51], v[190:193], v[198:201], v[48:51]
	v_mfma_f32_16x16x32_bf16 v[36:39], v[178:181], v[202:205], v[36:39]
	v_mfma_f32_16x16x32_bf16 v[36:39], v[182:185], v[206:209], v[36:39]
	v_mfma_f32_16x16x32_bf16 v[32:35], v[186:189], v[202:205], v[32:35]
	v_mfma_f32_16x16x32_bf16 v[32:35], v[190:193], v[206:209], v[32:35]
	v_mfma_f32_16x16x32_bf16 v[20:23], v[178:181], v[210:213], v[20:23]
	v_mfma_f32_16x16x32_bf16 v[20:23], v[182:185], v[214:217], v[20:23]
	v_mfma_f32_16x16x32_bf16 v[16:19], v[186:189], v[210:213], v[16:19]
	v_mfma_f32_16x16x32_bf16 v[16:19], v[190:193], v[214:217], v[16:19]
	v_mfma_f32_16x16x32_bf16 v[4:7], v[178:181], v[218:221], v[4:7]
	v_mfma_f32_16x16x32_bf16 v[4:7], v[182:185], v[222:225], v[4:7]
	v_mfma_f32_16x16x32_bf16 v[0:3], v[186:189], v[218:221], v[0:3]
	v_mfma_f32_16x16x32_bf16 v[0:3], v[190:193], v[222:225], v[0:3]
	s_barrier
	s_setprio 0
	s_add_i32 s65, 0, 0x18000
	v_add_u32_e32 v167, s65, v149
	s_add_i32 s66, 0, 0x1c000
	ds_read_b128 v[140:143], v167
	ds_read_b128 v[144:147], v167 offset:1024
	ds_read_b128 v[170:173], v167 offset:2048
	ds_read_b128 v[174:177], v167 offset:3072
	v_add_u32_e32 v167, s66, v149
	ds_read_b128 v[178:181], v167
	ds_read_b128 v[182:185], v167 offset:1024
	ds_read_b128 v[186:189], v167 offset:2048
	ds_read_b128 v[190:193], v167 offset:3072
	s_add_u32 s42, s42, 0x40000
	s_addc_u32 s43, s43, 0
	s_mov_b32 m0, s55
	v_lshl_add_u64 v[234:235], s[42:43], 0, v[134:135]
	ds_read_b128 v[194:197], v166 offset:32768
	ds_read_b128 v[198:201], v166 offset:33792
	ds_read_b128 v[202:205], v166 offset:34816
	ds_read_b128 v[206:209], v166 offset:35840
	ds_read_b128 v[210:213], v166 offset:36864
	ds_read_b128 v[214:217], v166 offset:37888
	ds_read_b128 v[218:221], v166 offset:38912
	ds_read_b128 v[222:225], v166 offset:39936
	global_load_lds_dwordx4 v[234:235], off
	v_lshl_add_u64 v[234:235], s[42:43], 0, v[130:131]
	s_mov_b32 m0, s56
	s_nop 0
	global_load_lds_dwordx4 v[234:235], off
	s_waitcnt vmcnt(8)
	s_waitcnt lgkmcnt(0)
	v_mfma_f32_16x16x32_bf16 v[124:127], v[140:143], v[194:197], v[124:127]
	v_mfma_f32_16x16x32_bf16 v[124:127], v[144:147], v[198:201], v[124:127]
	v_mfma_f32_16x16x32_bf16 v[120:123], v[170:173], v[194:197], v[120:123]
	v_mfma_f32_16x16x32_bf16 v[120:123], v[174:177], v[198:201], v[120:123]
	s_setprio 1
	s_barrier
	v_mfma_f32_16x16x32_bf16 v[108:111], v[140:143], v[202:205], v[108:111]
	v_mfma_f32_16x16x32_bf16 v[108:111], v[144:147], v[206:209], v[108:111]
	v_mfma_f32_16x16x32_bf16 v[104:107], v[170:173], v[202:205], v[104:107]
	v_mfma_f32_16x16x32_bf16 v[104:107], v[174:177], v[206:209], v[104:107]
	v_mfma_f32_16x16x32_bf16 v[92:95], v[140:143], v[210:213], v[92:95]
	v_mfma_f32_16x16x32_bf16 v[92:95], v[144:147], v[214:217], v[92:95]
	v_mfma_f32_16x16x32_bf16 v[88:91], v[170:173], v[210:213], v[88:91]
	v_mfma_f32_16x16x32_bf16 v[88:91], v[174:177], v[214:217], v[88:91]
	v_mfma_f32_16x16x32_bf16 v[76:79], v[140:143], v[218:221], v[76:79]
	v_mfma_f32_16x16x32_bf16 v[76:79], v[144:147], v[222:225], v[76:79]
	v_mfma_f32_16x16x32_bf16 v[72:75], v[170:173], v[218:221], v[72:75]
	v_mfma_f32_16x16x32_bf16 v[72:75], v[174:177], v[222:225], v[72:75]
	v_mfma_f32_16x16x32_bf16 v[116:119], v[178:181], v[194:197], v[116:119]
	v_mfma_f32_16x16x32_bf16 v[116:119], v[182:185], v[198:201], v[116:119]
	v_mfma_f32_16x16x32_bf16 v[112:115], v[186:189], v[194:197], v[112:115]
	v_mfma_f32_16x16x32_bf16 v[112:115], v[190:193], v[198:201], v[112:115]
	v_mfma_f32_16x16x32_bf16 v[100:103], v[178:181], v[202:205], v[100:103]
	v_mfma_f32_16x16x32_bf16 v[100:103], v[182:185], v[206:209], v[100:103]
	v_mfma_f32_16x16x32_bf16 v[96:99], v[186:189], v[202:205], v[96:99]
	v_mfma_f32_16x16x32_bf16 v[96:99], v[190:193], v[206:209], v[96:99]
	v_mfma_f32_16x16x32_bf16 v[84:87], v[178:181], v[210:213], v[84:87]
	v_mfma_f32_16x16x32_bf16 v[84:87], v[182:185], v[214:217], v[84:87]
	v_mfma_f32_16x16x32_bf16 v[80:83], v[186:189], v[210:213], v[80:83]
	v_mfma_f32_16x16x32_bf16 v[80:83], v[190:193], v[214:217], v[80:83]
	v_mfma_f32_16x16x32_bf16 v[68:71], v[178:181], v[218:221], v[68:71]
	v_mfma_f32_16x16x32_bf16 v[68:71], v[182:185], v[222:225], v[68:71]
	v_mfma_f32_16x16x32_bf16 v[64:67], v[186:189], v[218:221], v[64:67]
	v_mfma_f32_16x16x32_bf16 v[64:67], v[190:193], v[222:225], v[64:67]
	s_barrier
	s_setprio 0
	s_add_i32 s42, s65, s50
	v_lshl_add_u64 v[226:227], v[226:227], 0, s[36:37]
	s_mov_b32 m0, s42
	ds_read_b128 v[194:197], v166 offset:49152
	ds_read_b128 v[198:201], v166 offset:50176
	ds_read_b128 v[202:205], v166 offset:51200
	ds_read_b128 v[206:209], v166 offset:52224
	ds_read_b128 v[210:213], v166 offset:53248
	ds_read_b128 v[214:217], v166 offset:54272
	ds_read_b128 v[218:221], v166 offset:55296
	ds_read_b128 v[222:225], v166 offset:56320
	global_load_lds_dwordx4 v[226:227], off
	s_add_i32 m0, s42, 0x2000
	s_add_u32 s20, s20, 0x40080
	v_lshl_add_u64 v[226:227], v[228:229], 0, s[36:37]
	s_addc_u32 s21, s21, 0
	s_add_i32 s42, s66, s50
	global_load_lds_dwordx4 v[226:227], off
	v_lshl_add_u64 v[226:227], s[20:21], 0, v[132:133]
	s_mov_b32 m0, s42
	s_nop 0
	global_load_lds_dwordx4 v[226:227], off
	v_lshl_add_u64 v[226:227], s[20:21], 0, v[128:129]
	s_add_i32 m0, s42, 0x2000
	s_nop 0
	global_load_lds_dwordx4 v[226:227], off
	v_lshl_add_u64 v[226:227], v[230:231], 0, s[36:37]
	s_mov_b32 m0, s57
	s_nop 0
	global_load_lds_dwordx4 v[226:227], off
	v_lshl_add_u64 v[226:227], v[232:233], 0, s[36:37]
	s_mov_b32 m0, s58
	s_nop 0
	global_load_lds_dwordx4 v[226:227], off
	s_waitcnt vmcnt(8)
	s_waitcnt lgkmcnt(0)
	v_mfma_f32_16x16x32_bf16 v[60:63], v[140:143], v[194:197], v[60:63]
	v_mfma_f32_16x16x32_bf16 v[60:63], v[144:147], v[198:201], v[60:63]
	v_mfma_f32_16x16x32_bf16 v[56:59], v[170:173], v[194:197], v[56:59]
	v_mfma_f32_16x16x32_bf16 v[56:59], v[174:177], v[198:201], v[56:59]
	s_setprio 1
	s_barrier
	v_mfma_f32_16x16x32_bf16 v[44:47], v[140:143], v[202:205], v[44:47]
	v_mfma_f32_16x16x32_bf16 v[44:47], v[144:147], v[206:209], v[44:47]
	v_mfma_f32_16x16x32_bf16 v[40:43], v[170:173], v[202:205], v[40:43]
	v_mfma_f32_16x16x32_bf16 v[40:43], v[174:177], v[206:209], v[40:43]
	v_mfma_f32_16x16x32_bf16 v[28:31], v[140:143], v[210:213], v[28:31]
	v_mfma_f32_16x16x32_bf16 v[28:31], v[144:147], v[214:217], v[28:31]
	v_mfma_f32_16x16x32_bf16 v[24:27], v[170:173], v[210:213], v[24:27]
	v_mfma_f32_16x16x32_bf16 v[24:27], v[174:177], v[214:217], v[24:27]
	v_mfma_f32_16x16x32_bf16 v[12:15], v[140:143], v[218:221], v[12:15]
	v_mfma_f32_16x16x32_bf16 v[12:15], v[144:147], v[222:225], v[12:15]
	v_mfma_f32_16x16x32_bf16 v[8:11], v[170:173], v[218:221], v[8:11]
	v_mfma_f32_16x16x32_bf16 v[8:11], v[174:177], v[222:225], v[8:11]
	v_mfma_f32_16x16x32_bf16 v[52:55], v[178:181], v[194:197], v[52:55]
	v_mfma_f32_16x16x32_bf16 v[52:55], v[182:185], v[198:201], v[52:55]
	v_mfma_f32_16x16x32_bf16 v[48:51], v[186:189], v[194:197], v[48:51]
	v_mfma_f32_16x16x32_bf16 v[48:51], v[190:193], v[198:201], v[48:51]
	v_mfma_f32_16x16x32_bf16 v[36:39], v[178:181], v[202:205], v[36:39]
	v_mfma_f32_16x16x32_bf16 v[36:39], v[182:185], v[206:209], v[36:39]
	v_mfma_f32_16x16x32_bf16 v[32:35], v[186:189], v[202:205], v[32:35]
	v_mfma_f32_16x16x32_bf16 v[32:35], v[190:193], v[206:209], v[32:35]
	v_mfma_f32_16x16x32_bf16 v[20:23], v[178:181], v[210:213], v[20:23]
	v_mfma_f32_16x16x32_bf16 v[20:23], v[182:185], v[214:217], v[20:23]
	v_mfma_f32_16x16x32_bf16 v[16:19], v[186:189], v[210:213], v[16:19]
	v_mfma_f32_16x16x32_bf16 v[16:19], v[190:193], v[214:217], v[16:19]
	v_mfma_f32_16x16x32_bf16 v[4:7], v[178:181], v[218:221], v[4:7]
	v_mfma_f32_16x16x32_bf16 v[4:7], v[182:185], v[222:225], v[4:7]
	v_mfma_f32_16x16x32_bf16 v[0:3], v[186:189], v[218:221], v[0:3]
	v_mfma_f32_16x16x32_bf16 v[0:3], v[190:193], v[222:225], v[0:3]
	s_barrier
	s_setprio 0
	s_add_i32 s64, s64, 2
	s_add_u32 s62, s62, 0x100
	s_addc_u32 s63, s63, 0
	s_add_u32 s40, s40, 0x100
	s_addc_u32 s41, s41, 0
	s_cmp_gt_u32 s64, 13
	s_cbranch_scc0 .LBB0_478
	s_and_b64 vcc, exec, s[8:9]
	s_cbranch_vccz .LBB0_481
	s_barrier

.LBB0_575:
	s_add_i32 s54, s20, 2
	s_add_u32 s55, s42, 0x80
	s_addc_u32 s21, s43, 0
	s_add_i32 s74, 0, 0x10000
	s_cmp_eq_u32 s31, s20
	s_cselect_b32 s21, s51, s21
	s_cselect_b32 s20, s50, s55
	s_cselect_b32 s73, s53, s45
	s_cselect_b32 s72, s52, s44
	s_add_i32 s55, 0, 0x14000
	v_add_u32_e32 v124, s74, v207
	v_add_u32_e32 v166, s55, v207
	ds_read_b128 v[88:91], v124
	ds_read_b128 v[100:103], v124 offset:1024
	ds_read_b128 v[112:115], v124 offset:2048
	ds_read_b128 v[124:127], v124 offset:3072
	ds_read_b128 v[136:139], v166
	ds_read_b128 v[148:151], v166 offset:1024
	ds_read_b128 v[152:155], v166 offset:2048
	ds_read_b128 v[170:173], v166 offset:3072
	v_lshl_add_u64 v[166:167], s[42:43], 0, v[164:165]
	s_add_i32 m0, s61, 0xc000
	ds_read_b128 v[174:177], v211
	ds_read_b128 v[178:181], v211 offset:1024
	ds_read_b128 v[182:185], v211 offset:2048
	ds_read_b128 v[186:189], v211 offset:3072
	ds_read_b128 v[190:193], v211 offset:4096
	ds_read_b128 v[194:197], v211 offset:5120
	ds_read_b128 v[198:201], v211 offset:6144
	ds_read_b128 v[202:205], v211 offset:7168
	global_load_lds_dwordx4 v[166:167], off
	v_lshl_add_u64 v[166:167], s[42:43], 0, v[162:163]
	s_add_i32 m0, s61, 0xe000
	s_nop 0
	global_load_lds_dwordx4 v[166:167], off
	s_waitcnt vmcnt(8)
	s_waitcnt lgkmcnt(0)
	v_mfma_f32_16x16x32_bf16 v[144:147], v[88:91], v[174:177], v[144:147]
	v_mfma_f32_16x16x32_bf16 v[144:147], v[100:103], v[178:181], v[144:147]
	v_mfma_f32_16x16x32_bf16 v[140:143], v[112:115], v[174:177], v[140:143]
	v_mfma_f32_16x16x32_bf16 v[140:143], v[124:127], v[178:181], v[140:143]
	s_setprio 1
	s_barrier
	v_mfma_f32_16x16x32_bf16 v[120:123], v[88:91], v[182:185], v[120:123]
	v_mfma_f32_16x16x32_bf16 v[120:123], v[100:103], v[186:189], v[120:123]
	v_mfma_f32_16x16x32_bf16 v[116:119], v[112:115], v[182:185], v[116:119]
	v_mfma_f32_16x16x32_bf16 v[116:119], v[124:127], v[186:189], v[116:119]
	v_mfma_f32_16x16x32_bf16 v[96:99], v[88:91], v[190:193], v[96:99]
	v_mfma_f32_16x16x32_bf16 v[96:99], v[100:103], v[194:197], v[96:99]
	v_mfma_f32_16x16x32_bf16 v[92:95], v[112:115], v[190:193], v[92:95]
	v_mfma_f32_16x16x32_bf16 v[92:95], v[124:127], v[194:197], v[92:95]
	v_mfma_f32_16x16x32_bf16 v[76:79], v[88:91], v[198:201], v[76:79]
	v_mfma_f32_16x16x32_bf16 v[76:79], v[100:103], v[202:205], v[76:79]
	v_mfma_f32_16x16x32_bf16 v[72:75], v[112:115], v[198:201], v[72:75]
	v_mfma_f32_16x16x32_bf16 v[72:75], v[124:127], v[202:205], v[72:75]
	v_mfma_f32_16x16x32_bf16 v[132:135], v[136:139], v[174:177], v[132:135]
	v_mfma_f32_16x16x32_bf16 v[132:135], v[148:151], v[178:181], v[132:135]
	v_mfma_f32_16x16x32_bf16 v[128:131], v[152:155], v[174:177], v[128:131]
	v_mfma_f32_16x16x32_bf16 v[128:131], v[170:173], v[178:181], v[128:131]
	v_mfma_f32_16x16x32_bf16 v[108:111], v[136:139], v[182:185], v[108:111]
	v_mfma_f32_16x16x32_bf16 v[108:111], v[148:151], v[186:189], v[108:111]
	v_mfma_f32_16x16x32_bf16 v[104:107], v[152:155], v[182:185], v[104:107]
	v_mfma_f32_16x16x32_bf16 v[104:107], v[170:173], v[186:189], v[104:107]
	v_mfma_f32_16x16x32_bf16 v[84:87], v[136:139], v[190:193], v[84:87]
	v_mfma_f32_16x16x32_bf16 v[84:87], v[148:151], v[194:197], v[84:87]
	v_mfma_f32_16x16x32_bf16 v[80:83], v[152:155], v[190:193], v[80:83]
	v_mfma_f32_16x16x32_bf16 v[80:83], v[170:173], v[194:197], v[80:83]
	v_mfma_f32_16x16x32_bf16 v[68:71], v[136:139], v[198:201], v[68:71]
	v_mfma_f32_16x16x32_bf16 v[68:71], v[148:151], v[202:205], v[68:71]
	v_mfma_f32_16x16x32_bf16 v[64:67], v[152:155], v[198:201], v[64:67]
	v_mfma_f32_16x16x32_bf16 v[64:67], v[170:173], v[202:205], v[64:67]
	s_barrier
	s_setprio 0
	s_add_i32 s74, s74, s56
	v_lshl_add_u64 v[166:167], s[72:73], 0, v[168:169]
	s_mov_b32 m0, s74
	ds_read_b128 v[174:177], v211 offset:16384
	ds_read_b128 v[178:181], v211 offset:17408
	ds_read_b128 v[182:185], v211 offset:18432
	ds_read_b128 v[186:189], v211 offset:19456
	ds_read_b128 v[190:193], v211 offset:20480
	ds_read_b128 v[194:197], v211 offset:21504
	ds_read_b128 v[198:201], v211 offset:22528
	ds_read_b128 v[202:205], v211 offset:23552
	global_load_lds_dwordx4 v[166:167], off
	s_add_i32 m0, s74, 0x2000
	v_lshl_add_u64 v[212:213], s[72:73], 0, v[156:157]
	s_add_u32 s72, s72, s0
	s_addc_u32 s73, s73, 0
	s_add_i32 s55, s55, s56
	global_load_lds_dwordx4 v[212:213], off
	v_lshl_add_u64 v[214:215], s[72:73], 0, v[168:169]
	s_mov_b32 m0, s55
	v_lshl_add_u64 v[216:217], s[72:73], 0, v[156:157]
	global_load_lds_dwordx4 v[214:215], off
	s_add_i32 m0, s55, 0x2000
	v_lshl_add_u64 v[218:219], s[20:21], 0, v[160:161]
	global_load_lds_dwordx4 v[216:217], off
	s_mov_b32 m0, s61
	v_lshl_add_u64 v[220:221], s[20:21], 0, v[158:159]
	global_load_lds_dwordx4 v[218:219], off
	s_mov_b32 m0, s62
	s_nop 0
	global_load_lds_dwordx4 v[220:221], off
	s_waitcnt vmcnt(8)
	s_waitcnt lgkmcnt(0)
	v_mfma_f32_16x16x32_bf16 v[60:63], v[88:91], v[174:177], v[60:63]
	v_mfma_f32_16x16x32_bf16 v[60:63], v[100:103], v[178:181], v[60:63]
	v_mfma_f32_16x16x32_bf16 v[56:59], v[112:115], v[174:177], v[56:59]
	v_mfma_f32_16x16x32_bf16 v[56:59], v[124:127], v[178:181], v[56:59]
	s_setprio 1
	s_barrier
	v_mfma_f32_16x16x32_bf16 v[44:47], v[88:91], v[182:185], v[44:47]
	v_mfma_f32_16x16x32_bf16 v[44:47], v[100:103], v[186:189], v[44:47]
	v_mfma_f32_16x16x32_bf16 v[40:43], v[112:115], v[182:185], v[40:43]
	v_mfma_f32_16x16x32_bf16 v[40:43], v[124:127], v[186:189], v[40:43]
	v_mfma_f32_16x16x32_bf16 v[28:31], v[88:91], v[190:193], v[28:31]
	v_mfma_f32_16x16x32_bf16 v[28:31], v[100:103], v[194:197], v[28:31]
	v_mfma_f32_16x16x32_bf16 v[24:27], v[112:115], v[190:193], v[24:27]
	v_mfma_f32_16x16x32_bf16 v[24:27], v[124:127], v[194:197], v[24:27]
	v_mfma_f32_16x16x32_bf16 v[12:15], v[88:91], v[198:201], v[12:15]
	v_mfma_f32_16x16x32_bf16 v[12:15], v[100:103], v[202:205], v[12:15]
	v_mfma_f32_16x16x32_bf16 v[8:11], v[112:115], v[198:201], v[8:11]
	v_mfma_f32_16x16x32_bf16 v[8:11], v[124:127], v[202:205], v[8:11]
	v_mfma_f32_16x16x32_bf16 v[52:55], v[136:139], v[174:177], v[52:55]
	v_mfma_f32_16x16x32_bf16 v[52:55], v[148:151], v[178:181], v[52:55]
	v_mfma_f32_16x16x32_bf16 v[48:51], v[152:155], v[174:177], v[48:51]
	v_mfma_f32_16x16x32_bf16 v[48:51], v[170:173], v[178:181], v[48:51]
	v_mfma_f32_16x16x32_bf16 v[36:39], v[136:139], v[182:185], v[36:39]
	v_mfma_f32_16x16x32_bf16 v[36:39], v[148:151], v[186:189], v[36:39]
	v_mfma_f32_16x16x32_bf16 v[32:35], v[152:155], v[182:185], v[32:35]
	v_mfma_f32_16x16x32_bf16 v[32:35], v[170:173], v[186:189], v[32:35]
	v_mfma_f32_16x16x32_bf16 v[20:23], v[136:139], v[190:193], v[20:23]
	v_mfma_f32_16x16x32_bf16 v[20:23], v[148:151], v[194:197], v[20:23]
	v_mfma_f32_16x16x32_bf16 v[16:19], v[152:155], v[190:193], v[16:19]
	v_mfma_f32_16x16x32_bf16 v[16:19], v[170:173], v[194:197], v[16:19]
	v_mfma_f32_16x16x32_bf16 v[4:7], v[136:139], v[198:201], v[4:7]
	v_mfma_f32_16x16x32_bf16 v[4:7], v[148:151], v[202:205], v[4:7]
	v_mfma_f32_16x16x32_bf16 v[0:3], v[152:155], v[198:201], v[0:3]
	v_mfma_f32_16x16x32_bf16 v[0:3], v[170:173], v[202:205], v[0:3]
	s_barrier
	s_setprio 0
	s_add_i32 s55, 0, 0x18000
	s_add_i32 s72, 0, 0x1c000
	v_add_u32_e32 v124, s55, v207
	v_add_u32_e32 v170, s72, v207
	ds_read_b128 v[88:91], v124
	ds_read_b128 v[100:103], v124 offset:1024
	ds_read_b128 v[112:115], v124 offset:2048
	ds_read_b128 v[124:127], v124 offset:3072
	ds_read_b128 v[136:139], v170
	ds_read_b128 v[148:151], v170 offset:1024
	ds_read_b128 v[152:155], v170 offset:2048
	ds_read_b128 v[170:173], v170 offset:3072
	s_add_u32 s20, s20, s0
	s_addc_u32 s21, s21, 0
	s_mov_b32 m0, s63
	v_lshl_add_u64 v[222:223], s[20:21], 0, v[160:161]
	ds_read_b128 v[174:177], v211 offset:32768
	ds_read_b128 v[178:181], v211 offset:33792
	ds_read_b128 v[182:185], v211 offset:34816
	ds_read_b128 v[186:189], v211 offset:35840
	ds_read_b128 v[190:193], v211 offset:36864
	ds_read_b128 v[194:197], v211 offset:37888
	ds_read_b128 v[198:201], v211 offset:38912
	ds_read_b128 v[202:205], v211 offset:39936
	global_load_lds_dwordx4 v[222:223], off
	v_lshl_add_u64 v[222:223], s[20:21], 0, v[158:159]
	s_mov_b32 m0, s64
	s_nop 0
	global_load_lds_dwordx4 v[222:223], off
	s_waitcnt vmcnt(8)
	s_waitcnt lgkmcnt(0)
	v_mfma_f32_16x16x32_bf16 v[144:147], v[88:91], v[174:177], v[144:147]
	v_mfma_f32_16x16x32_bf16 v[144:147], v[100:103], v[178:181], v[144:147]
	v_mfma_f32_16x16x32_bf16 v[140:143], v[112:115], v[174:177], v[140:143]
	v_mfma_f32_16x16x32_bf16 v[140:143], v[124:127], v[178:181], v[140:143]
	s_setprio 1
	s_barrier
	v_mfma_f32_16x16x32_bf16 v[120:123], v[88:91], v[182:185], v[120:123]
	v_mfma_f32_16x16x32_bf16 v[120:123], v[100:103], v[186:189], v[120:123]
	v_mfma_f32_16x16x32_bf16 v[116:119], v[112:115], v[182:185], v[116:119]
	v_mfma_f32_16x16x32_bf16 v[116:119], v[124:127], v[186:189], v[116:119]
	v_mfma_f32_16x16x32_bf16 v[96:99], v[88:91], v[190:193], v[96:99]
	v_mfma_f32_16x16x32_bf16 v[96:99], v[100:103], v[194:197], v[96:99]
	v_mfma_f32_16x16x32_bf16 v[92:95], v[112:115], v[190:193], v[92:95]
	v_mfma_f32_16x16x32_bf16 v[92:95], v[124:127], v[194:197], v[92:95]
	v_mfma_f32_16x16x32_bf16 v[76:79], v[88:91], v[198:201], v[76:79]
	v_mfma_f32_16x16x32_bf16 v[76:79], v[100:103], v[202:205], v[76:79]
	v_mfma_f32_16x16x32_bf16 v[72:75], v[112:115], v[198:201], v[72:75]
	v_mfma_f32_16x16x32_bf16 v[72:75], v[124:127], v[202:205], v[72:75]
	v_mfma_f32_16x16x32_bf16 v[132:135], v[136:139], v[174:177], v[132:135]
	v_mfma_f32_16x16x32_bf16 v[132:135], v[148:151], v[178:181], v[132:135]
	v_mfma_f32_16x16x32_bf16 v[128:131], v[152:155], v[174:177], v[128:131]
	v_mfma_f32_16x16x32_bf16 v[128:131], v[170:173], v[178:181], v[128:131]
	v_mfma_f32_16x16x32_bf16 v[108:111], v[136:139], v[182:185], v[108:111]
	v_mfma_f32_16x16x32_bf16 v[108:111], v[148:151], v[186:189], v[108:111]
	v_mfma_f32_16x16x32_bf16 v[104:107], v[152:155], v[182:185], v[104:107]
	v_mfma_f32_16x16x32_bf16 v[104:107], v[170:173], v[186:189], v[104:107]
	v_mfma_f32_16x16x32_bf16 v[84:87], v[136:139], v[190:193], v[84:87]
	v_mfma_f32_16x16x32_bf16 v[84:87], v[148:151], v[194:197], v[84:87]
	v_mfma_f32_16x16x32_bf16 v[80:83], v[152:155], v[190:193], v[80:83]
	v_mfma_f32_16x16x32_bf16 v[80:83], v[170:173], v[194:197], v[80:83]
	v_mfma_f32_16x16x32_bf16 v[68:71], v[136:139], v[198:201], v[68:71]
	v_mfma_f32_16x16x32_bf16 v[68:71], v[148:151], v[202:205], v[68:71]
	v_mfma_f32_16x16x32_bf16 v[64:67], v[152:155], v[198:201], v[64:67]
	v_mfma_f32_16x16x32_bf16 v[64:67], v[170:173], v[202:205], v[64:67]
	s_barrier
	s_setprio 0
	s_add_i32 s20, s55, s56
	v_lshl_add_u64 v[166:167], v[166:167], 0, s[36:37]
	s_mov_b32 m0, s20
	ds_read_b128 v[174:177], v211 offset:49152
	ds_read_b128 v[178:181], v211 offset:50176
	ds_read_b128 v[182:185], v211 offset:51200
	ds_read_b128 v[186:189], v211 offset:52224
	ds_read_b128 v[190:193], v211 offset:53248
	ds_read_b128 v[194:197], v211 offset:54272
	ds_read_b128 v[198:201], v211 offset:55296
	ds_read_b128 v[202:205], v211 offset:56320
	global_load_lds_dwordx4 v[166:167], off
	v_lshl_add_u64 v[166:167], v[212:213], 0, s[36:37]
	s_add_i32 m0, s20, 0x2000
	s_add_i32 s20, s72, s56
	global_load_lds_dwordx4 v[166:167], off
	v_lshl_add_u64 v[166:167], v[214:215], 0, s[36:37]
	s_mov_b32 m0, s20
	s_nop 0
	global_load_lds_dwordx4 v[166:167], off
	v_lshl_add_u64 v[166:167], v[216:217], 0, s[36:37]
	s_add_i32 m0, s20, 0x2000
	s_nop 0
	global_load_lds_dwordx4 v[166:167], off
	v_lshl_add_u64 v[166:167], v[218:219], 0, s[36:37]
	s_mov_b32 m0, s66
	s_nop 0
	global_load_lds_dwordx4 v[166:167], off
	v_lshl_add_u64 v[166:167], v[220:221], 0, s[36:37]
	s_mov_b32 m0, s67
	s_nop 0
	global_load_lds_dwordx4 v[166:167], off
	s_waitcnt vmcnt(8)
	s_waitcnt lgkmcnt(0)
	v_mfma_f32_16x16x32_bf16 v[60:63], v[88:91], v[174:177], v[60:63]
	v_mfma_f32_16x16x32_bf16 v[60:63], v[100:103], v[178:181], v[60:63]
	v_mfma_f32_16x16x32_bf16 v[56:59], v[112:115], v[174:177], v[56:59]
	v_mfma_f32_16x16x32_bf16 v[56:59], v[124:127], v[178:181], v[56:59]
	s_setprio 1
	s_barrier
	v_mfma_f32_16x16x32_bf16 v[44:47], v[88:91], v[182:185], v[44:47]
	v_mfma_f32_16x16x32_bf16 v[44:47], v[100:103], v[186:189], v[44:47]
	v_mfma_f32_16x16x32_bf16 v[40:43], v[112:115], v[182:185], v[40:43]
	v_mfma_f32_16x16x32_bf16 v[40:43], v[124:127], v[186:189], v[40:43]
	v_mfma_f32_16x16x32_bf16 v[28:31], v[88:91], v[190:193], v[28:31]
	v_mfma_f32_16x16x32_bf16 v[28:31], v[100:103], v[194:197], v[28:31]
	v_mfma_f32_16x16x32_bf16 v[24:27], v[112:115], v[190:193], v[24:27]
	v_mfma_f32_16x16x32_bf16 v[24:27], v[124:127], v[194:197], v[24:27]
	v_mfma_f32_16x16x32_bf16 v[12:15], v[88:91], v[198:201], v[12:15]
	v_mfma_f32_16x16x32_bf16 v[12:15], v[100:103], v[202:205], v[12:15]
	v_mfma_f32_16x16x32_bf16 v[8:11], v[112:115], v[198:201], v[8:11]
	v_mfma_f32_16x16x32_bf16 v[8:11], v[124:127], v[202:205], v[8:11]
	v_mfma_f32_16x16x32_bf16 v[52:55], v[136:139], v[174:177], v[52:55]
	v_mfma_f32_16x16x32_bf16 v[52:55], v[148:151], v[178:181], v[52:55]
	v_mfma_f32_16x16x32_bf16 v[48:51], v[152:155], v[174:177], v[48:51]
	v_mfma_f32_16x16x32_bf16 v[48:51], v[170:173], v[178:181], v[48:51]
	v_mfma_f32_16x16x32_bf16 v[36:39], v[136:139], v[182:185], v[36:39]
	v_mfma_f32_16x16x32_bf16 v[36:39], v[148:151], v[186:189], v[36:39]
	v_mfma_f32_16x16x32_bf16 v[32:35], v[152:155], v[182:185], v[32:35]
	v_mfma_f32_16x16x32_bf16 v[32:35], v[170:173], v[186:189], v[32:35]
	v_mfma_f32_16x16x32_bf16 v[20:23], v[136:139], v[190:193], v[20:23]
	v_mfma_f32_16x16x32_bf16 v[20:23], v[148:151], v[194:197], v[20:23]
	v_mfma_f32_16x16x32_bf16 v[16:19], v[152:155], v[190:193], v[16:19]
	v_mfma_f32_16x16x32_bf16 v[16:19], v[170:173], v[194:197], v[16:19]
	v_mfma_f32_16x16x32_bf16 v[4:7], v[136:139], v[198:201], v[4:7]
	v_mfma_f32_16x16x32_bf16 v[4:7], v[148:151], v[202:205], v[4:7]
	v_mfma_f32_16x16x32_bf16 v[0:3], v[152:155], v[198:201], v[0:3]
	v_mfma_f32_16x16x32_bf16 v[0:3], v[170:173], v[202:205], v[0:3]
	s_barrier
	s_setprio 0
	s_add_u32 s44, s44, 0x100
	s_addc_u32 s45, s45, 0
	s_add_u32 s42, s42, 0x100
	s_addc_u32 s43, s43, 0
	s_cmp_ge_u32 s54, s3
	s_mov_b32 s20, s54
	s_cbranch_scc0 .LBB0_575
	s_and_b64 vcc, exec, s[16:17]
	s_cbranch_vccz .LBB0_578
	s_barrier

.LBB0_692:
	s_add_u32 s20, s40, 0xfffc0080
	s_addc_u32 s21, s41, -1
	s_add_i32 s71, 0, 0x10000
	s_cmp_eq_u32 s70, 12
	s_cselect_b32 s51, s43, s21
	s_cselect_b32 s50, s66, s20
	s_cselect_b32 s21, s19, s69
	s_cselect_b32 s20, s67, s68
	s_add_i32 s74, 0, 0x14000
	v_add_u32_e32 v150, s71, v156
	v_add_u32_e32 v188, s74, v156
	ds_read_b128 v[138:141], v150
	ds_read_b128 v[142:145], v150 offset:1024
	ds_read_b128 v[146:149], v150 offset:2048
	ds_read_b128 v[150:153], v150 offset:3072
	ds_read_b128 v[176:179], v188
	ds_read_b128 v[180:183], v188 offset:1024
	ds_read_b128 v[184:187], v188 offset:2048
	ds_read_b128 v[188:191], v188 offset:3072
	v_lshl_add_u64 v[224:225], s[40:41], 0, v[136:137]
	s_add_i32 m0, s57, 0xc000
	ds_read_b128 v[192:195], v175
	ds_read_b128 v[196:199], v175 offset:1024
	ds_read_b128 v[200:203], v175 offset:2048
	ds_read_b128 v[204:207], v175 offset:3072
	ds_read_b128 v[208:211], v175 offset:4096
	ds_read_b128 v[212:215], v175 offset:5120
	ds_read_b128 v[216:219], v175 offset:6144
	ds_read_b128 v[220:223], v175 offset:7168
	global_load_lds_dwordx4 v[224:225], off
	v_lshl_add_u64 v[224:225], s[40:41], 0, v[134:135]
	s_add_i32 m0, s57, 0xe000
	s_nop 0
	global_load_lds_dwordx4 v[224:225], off
	s_waitcnt vmcnt(8)
	s_waitcnt lgkmcnt(0)
	v_mfma_f32_16x16x32_bf16 v[124:127], v[138:141], v[192:195], v[124:127]
	v_mfma_f32_16x16x32_bf16 v[124:127], v[142:145], v[196:199], v[124:127]
	v_mfma_f32_16x16x32_bf16 v[112:115], v[146:149], v[192:195], v[112:115]
	v_mfma_f32_16x16x32_bf16 v[112:115], v[150:153], v[196:199], v[112:115]
	s_setprio 1
	s_barrier
	v_mfma_f32_16x16x32_bf16 v[108:111], v[138:141], v[200:203], v[108:111]
	v_mfma_f32_16x16x32_bf16 v[108:111], v[142:145], v[204:207], v[108:111]
	v_mfma_f32_16x16x32_bf16 v[96:99], v[146:149], v[200:203], v[96:99]
	v_mfma_f32_16x16x32_bf16 v[96:99], v[150:153], v[204:207], v[96:99]
	v_mfma_f32_16x16x32_bf16 v[92:95], v[138:141], v[208:211], v[92:95]
	v_mfma_f32_16x16x32_bf16 v[92:95], v[142:145], v[212:215], v[92:95]
	v_mfma_f32_16x16x32_bf16 v[80:83], v[146:149], v[208:211], v[80:83]
	v_mfma_f32_16x16x32_bf16 v[80:83], v[150:153], v[212:215], v[80:83]
	v_mfma_f32_16x16x32_bf16 v[76:79], v[138:141], v[216:219], v[76:79]
	v_mfma_f32_16x16x32_bf16 v[76:79], v[142:145], v[220:223], v[76:79]
	v_mfma_f32_16x16x32_bf16 v[64:67], v[146:149], v[216:219], v[64:67]
	v_mfma_f32_16x16x32_bf16 v[64:67], v[150:153], v[220:223], v[64:67]
	v_mfma_f32_16x16x32_bf16 v[120:123], v[176:179], v[192:195], v[120:123]
	v_mfma_f32_16x16x32_bf16 v[120:123], v[180:183], v[196:199], v[120:123]
	v_mfma_f32_16x16x32_bf16 v[116:119], v[184:187], v[192:195], v[116:119]
	v_mfma_f32_16x16x32_bf16 v[116:119], v[188:191], v[196:199], v[116:119]
	v_mfma_f32_16x16x32_bf16 v[104:107], v[176:179], v[200:203], v[104:107]
	v_mfma_f32_16x16x32_bf16 v[104:107], v[180:183], v[204:207], v[104:107]
	v_mfma_f32_16x16x32_bf16 v[100:103], v[184:187], v[200:203], v[100:103]
	v_mfma_f32_16x16x32_bf16 v[100:103], v[188:191], v[204:207], v[100:103]
	v_mfma_f32_16x16x32_bf16 v[88:91], v[176:179], v[208:211], v[88:91]
	v_mfma_f32_16x16x32_bf16 v[88:91], v[180:183], v[212:215], v[88:91]
	v_mfma_f32_16x16x32_bf16 v[84:87], v[184:187], v[208:211], v[84:87]
	v_mfma_f32_16x16x32_bf16 v[84:87], v[188:191], v[212:215], v[84:87]
	v_mfma_f32_16x16x32_bf16 v[72:75], v[176:179], v[216:219], v[72:75]
	v_mfma_f32_16x16x32_bf16 v[72:75], v[180:183], v[220:223], v[72:75]
	v_mfma_f32_16x16x32_bf16 v[68:71], v[184:187], v[216:219], v[68:71]
	v_mfma_f32_16x16x32_bf16 v[68:71], v[188:191], v[220:223], v[68:71]
	s_barrier
	s_setprio 0
	s_add_i32 s71, s71, s54
	v_lshl_add_u64 v[224:225], s[20:21], 0, v[168:169]
	s_mov_b32 m0, s71
	ds_read_b128 v[192:195], v175 offset:16384
	ds_read_b128 v[196:199], v175 offset:17408
	ds_read_b128 v[200:203], v175 offset:18432
	ds_read_b128 v[204:207], v175 offset:19456
	ds_read_b128 v[208:211], v175 offset:20480
	ds_read_b128 v[212:215], v175 offset:21504
	ds_read_b128 v[216:219], v175 offset:22528
	ds_read_b128 v[220:223], v175 offset:23552
	global_load_lds_dwordx4 v[224:225], off
	s_add_i32 m0, s71, 0x2000
	s_add_u32 s72, s20, 0x40000
	v_lshl_add_u64 v[226:227], s[20:21], 0, v[128:129]
	s_addc_u32 s73, s21, 0
	s_add_i32 s71, s74, s54
	global_load_lds_dwordx4 v[226:227], off
	v_lshl_add_u64 v[228:229], s[72:73], 0, v[168:169]
	s_mov_b32 m0, s71
	v_lshl_add_u64 v[230:231], s[50:51], 0, v[130:131]
	global_load_lds_dwordx4 v[228:229], off
	v_lshl_add_u64 v[228:229], s[72:73], 0, v[128:129]
	s_add_i32 m0, s71, 0x2000
	s_nop 0
	global_load_lds_dwordx4 v[228:229], off
	v_lshl_add_u64 v[228:229], s[50:51], 0, v[132:133]
	s_mov_b32 m0, s57
	s_nop 0
	global_load_lds_dwordx4 v[228:229], off
	s_mov_b32 m0, s58
	s_nop 0
	global_load_lds_dwordx4 v[230:231], off
	s_waitcnt vmcnt(8)
	s_waitcnt lgkmcnt(0)
	v_mfma_f32_16x16x32_bf16 v[60:63], v[138:141], v[192:195], v[60:63]
	v_mfma_f32_16x16x32_bf16 v[60:63], v[142:145], v[196:199], v[60:63]
	v_mfma_f32_16x16x32_bf16 v[48:51], v[146:149], v[192:195], v[48:51]
	v_mfma_f32_16x16x32_bf16 v[48:51], v[150:153], v[196:199], v[48:51]
	s_setprio 1
	s_barrier
	v_mfma_f32_16x16x32_bf16 v[44:47], v[138:141], v[200:203], v[44:47]
	v_mfma_f32_16x16x32_bf16 v[44:47], v[142:145], v[204:207], v[44:47]
	v_mfma_f32_16x16x32_bf16 v[32:35], v[146:149], v[200:203], v[32:35]
	v_mfma_f32_16x16x32_bf16 v[32:35], v[150:153], v[204:207], v[32:35]
	v_mfma_f32_16x16x32_bf16 v[28:31], v[138:141], v[208:211], v[28:31]
	v_mfma_f32_16x16x32_bf16 v[28:31], v[142:145], v[212:215], v[28:31]
	v_mfma_f32_16x16x32_bf16 v[16:19], v[146:149], v[208:211], v[16:19]
	v_mfma_f32_16x16x32_bf16 v[16:19], v[150:153], v[212:215], v[16:19]
	v_mfma_f32_16x16x32_bf16 v[12:15], v[138:141], v[216:219], v[12:15]
	v_mfma_f32_16x16x32_bf16 v[12:15], v[142:145], v[220:223], v[12:15]
	v_mfma_f32_16x16x32_bf16 v[4:7], v[146:149], v[216:219], v[4:7]
	v_mfma_f32_16x16x32_bf16 v[4:7], v[150:153], v[220:223], v[4:7]
	v_mfma_f32_16x16x32_bf16 v[56:59], v[176:179], v[192:195], v[56:59]
	v_mfma_f32_16x16x32_bf16 v[56:59], v[180:183], v[196:199], v[56:59]
	v_mfma_f32_16x16x32_bf16 v[52:55], v[184:187], v[192:195], v[52:55]
	v_mfma_f32_16x16x32_bf16 v[52:55], v[188:191], v[196:199], v[52:55]
	v_mfma_f32_16x16x32_bf16 v[40:43], v[176:179], v[200:203], v[40:43]
	v_mfma_f32_16x16x32_bf16 v[40:43], v[180:183], v[204:207], v[40:43]
	v_mfma_f32_16x16x32_bf16 v[36:39], v[184:187], v[200:203], v[36:39]
	v_mfma_f32_16x16x32_bf16 v[36:39], v[188:191], v[204:207], v[36:39]
	v_mfma_f32_16x16x32_bf16 v[24:27], v[176:179], v[208:211], v[24:27]
	v_mfma_f32_16x16x32_bf16 v[24:27], v[180:183], v[212:215], v[24:27]
	v_mfma_f32_16x16x32_bf16 v[20:23], v[184:187], v[208:211], v[20:23]
	v_mfma_f32_16x16x32_bf16 v[20:23], v[188:191], v[212:215], v[20:23]
	v_mfma_f32_16x16x32_bf16 v[8:11], v[176:179], v[216:219], v[8:11]
	v_mfma_f32_16x16x32_bf16 v[8:11], v[180:183], v[220:223], v[8:11]
	v_mfma_f32_16x16x32_bf16 v[0:3], v[184:187], v[216:219], v[0:3]
	v_mfma_f32_16x16x32_bf16 v[0:3], v[188:191], v[220:223], v[0:3]
	s_barrier
	s_setprio 0
	s_add_i32 s71, 0, 0x18000
	s_add_i32 s72, 0, 0x1c000
	v_add_u32_e32 v150, s71, v156
	v_add_u32_e32 v188, s72, v156
	ds_read_b128 v[138:141], v150
	ds_read_b128 v[142:145], v150 offset:1024
	ds_read_b128 v[146:149], v150 offset:2048
	ds_read_b128 v[150:153], v150 offset:3072
	ds_read_b128 v[176:179], v188
	ds_read_b128 v[180:183], v188 offset:1024
	ds_read_b128 v[184:187], v188 offset:2048
	ds_read_b128 v[188:191], v188 offset:3072
	s_add_u32 s50, s50, 0x40000
	s_addc_u32 s51, s51, 0
	s_mov_b32 m0, s59
	v_lshl_add_u64 v[232:233], s[50:51], 0, v[132:133]
	ds_read_b128 v[192:195], v175 offset:32768
	ds_read_b128 v[196:199], v175 offset:33792
	ds_read_b128 v[200:203], v175 offset:34816
	ds_read_b128 v[204:207], v175 offset:35840
	ds_read_b128 v[208:211], v175 offset:36864
	ds_read_b128 v[212:215], v175 offset:37888
	ds_read_b128 v[216:219], v175 offset:38912
	ds_read_b128 v[220:223], v175 offset:39936
	global_load_lds_dwordx4 v[232:233], off
	v_lshl_add_u64 v[232:233], s[50:51], 0, v[130:131]
	s_mov_b32 m0, s60
	s_nop 0
	global_load_lds_dwordx4 v[232:233], off
	s_waitcnt vmcnt(8)
	s_waitcnt lgkmcnt(0)
	v_mfma_f32_16x16x32_bf16 v[124:127], v[138:141], v[192:195], v[124:127]
	v_mfma_f32_16x16x32_bf16 v[124:127], v[142:145], v[196:199], v[124:127]
	v_mfma_f32_16x16x32_bf16 v[112:115], v[146:149], v[192:195], v[112:115]
	v_mfma_f32_16x16x32_bf16 v[112:115], v[150:153], v[196:199], v[112:115]
	s_setprio 1
	s_barrier
	v_mfma_f32_16x16x32_bf16 v[108:111], v[138:141], v[200:203], v[108:111]
	v_mfma_f32_16x16x32_bf16 v[108:111], v[142:145], v[204:207], v[108:111]
	v_mfma_f32_16x16x32_bf16 v[96:99], v[146:149], v[200:203], v[96:99]
	v_mfma_f32_16x16x32_bf16 v[96:99], v[150:153], v[204:207], v[96:99]
	v_mfma_f32_16x16x32_bf16 v[92:95], v[138:141], v[208:211], v[92:95]
	v_mfma_f32_16x16x32_bf16 v[92:95], v[142:145], v[212:215], v[92:95]
	v_mfma_f32_16x16x32_bf16 v[80:83], v[146:149], v[208:211], v[80:83]
	v_mfma_f32_16x16x32_bf16 v[80:83], v[150:153], v[212:215], v[80:83]
	v_mfma_f32_16x16x32_bf16 v[76:79], v[138:141], v[216:219], v[76:79]
	v_mfma_f32_16x16x32_bf16 v[76:79], v[142:145], v[220:223], v[76:79]
	v_mfma_f32_16x16x32_bf16 v[64:67], v[146:149], v[216:219], v[64:67]
	v_mfma_f32_16x16x32_bf16 v[64:67], v[150:153], v[220:223], v[64:67]
	v_mfma_f32_16x16x32_bf16 v[120:123], v[176:179], v[192:195], v[120:123]
	v_mfma_f32_16x16x32_bf16 v[120:123], v[180:183], v[196:199], v[120:123]
	v_mfma_f32_16x16x32_bf16 v[116:119], v[184:187], v[192:195], v[116:119]
	v_mfma_f32_16x16x32_bf16 v[116:119], v[188:191], v[196:199], v[116:119]
	v_mfma_f32_16x16x32_bf16 v[104:107], v[176:179], v[200:203], v[104:107]
	v_mfma_f32_16x16x32_bf16 v[104:107], v[180:183], v[204:207], v[104:107]
	v_mfma_f32_16x16x32_bf16 v[100:103], v[184:187], v[200:203], v[100:103]
	v_mfma_f32_16x16x32_bf16 v[100:103], v[188:191], v[204:207], v[100:103]
	v_mfma_f32_16x16x32_bf16 v[88:91], v[176:179], v[208:211], v[88:91]
	v_mfma_f32_16x16x32_bf16 v[88:91], v[180:183], v[212:215], v[88:91]
	v_mfma_f32_16x16x32_bf16 v[84:87], v[184:187], v[208:211], v[84:87]
	v_mfma_f32_16x16x32_bf16 v[84:87], v[188:191], v[212:215], v[84:87]
	v_mfma_f32_16x16x32_bf16 v[72:75], v[176:179], v[216:219], v[72:75]
	v_mfma_f32_16x16x32_bf16 v[72:75], v[180:183], v[220:223], v[72:75]
	v_mfma_f32_16x16x32_bf16 v[68:71], v[184:187], v[216:219], v[68:71]
	v_mfma_f32_16x16x32_bf16 v[68:71], v[188:191], v[220:223], v[68:71]
	s_barrier
	s_setprio 0
	s_add_i32 s50, s71, s54
	v_lshl_add_u64 v[224:225], v[224:225], 0, s[36:37]
	s_mov_b32 m0, s50
	ds_read_b128 v[192:195], v175 offset:49152
	ds_read_b128 v[196:199], v175 offset:50176
	ds_read_b128 v[200:203], v175 offset:51200
	ds_read_b128 v[204:207], v175 offset:52224
	ds_read_b128 v[208:211], v175 offset:53248
	ds_read_b128 v[212:215], v175 offset:54272
	ds_read_b128 v[216:219], v175 offset:55296
	ds_read_b128 v[220:223], v175 offset:56320
	global_load_lds_dwordx4 v[224:225], off
	s_add_i32 m0, s50, 0x2000
	s_add_u32 s20, s20, 0x40080
	v_lshl_add_u64 v[224:225], v[226:227], 0, s[36:37]
	s_addc_u32 s21, s21, 0
	s_add_i32 s50, s72, s54
	global_load_lds_dwordx4 v[224:225], off
	v_lshl_add_u64 v[224:225], s[20:21], 0, v[168:169]
	s_mov_b32 m0, s50
	s_nop 0
	global_load_lds_dwordx4 v[224:225], off
	v_lshl_add_u64 v[224:225], s[20:21], 0, v[128:129]
	s_add_i32 m0, s50, 0x2000
	s_nop 0
	global_load_lds_dwordx4 v[224:225], off
	v_lshl_add_u64 v[224:225], v[228:229], 0, s[36:37]
	s_mov_b32 m0, s61
	s_nop 0
	global_load_lds_dwordx4 v[224:225], off
	v_lshl_add_u64 v[224:225], v[230:231], 0, s[36:37]
	s_mov_b32 m0, s62
	s_nop 0
	global_load_lds_dwordx4 v[224:225], off
	s_waitcnt vmcnt(8)
	s_waitcnt lgkmcnt(0)
	v_mfma_f32_16x16x32_bf16 v[60:63], v[138:141], v[192:195], v[60:63]
	v_mfma_f32_16x16x32_bf16 v[60:63], v[142:145], v[196:199], v[60:63]
	v_mfma_f32_16x16x32_bf16 v[48:51], v[146:149], v[192:195], v[48:51]
	v_mfma_f32_16x16x32_bf16 v[48:51], v[150:153], v[196:199], v[48:51]
	s_setprio 1
	s_barrier
	v_mfma_f32_16x16x32_bf16 v[44:47], v[138:141], v[200:203], v[44:47]
	v_mfma_f32_16x16x32_bf16 v[44:47], v[142:145], v[204:207], v[44:47]
	v_mfma_f32_16x16x32_bf16 v[32:35], v[146:149], v[200:203], v[32:35]
	v_mfma_f32_16x16x32_bf16 v[32:35], v[150:153], v[204:207], v[32:35]
	v_mfma_f32_16x16x32_bf16 v[28:31], v[138:141], v[208:211], v[28:31]
	v_mfma_f32_16x16x32_bf16 v[28:31], v[142:145], v[212:215], v[28:31]
	v_mfma_f32_16x16x32_bf16 v[16:19], v[146:149], v[208:211], v[16:19]
	v_mfma_f32_16x16x32_bf16 v[16:19], v[150:153], v[212:215], v[16:19]
	v_mfma_f32_16x16x32_bf16 v[12:15], v[138:141], v[216:219], v[12:15]
	v_mfma_f32_16x16x32_bf16 v[12:15], v[142:145], v[220:223], v[12:15]
	v_mfma_f32_16x16x32_bf16 v[4:7], v[146:149], v[216:219], v[4:7]
	v_mfma_f32_16x16x32_bf16 v[4:7], v[150:153], v[220:223], v[4:7]
	v_mfma_f32_16x16x32_bf16 v[56:59], v[176:179], v[192:195], v[56:59]
	v_mfma_f32_16x16x32_bf16 v[56:59], v[180:183], v[196:199], v[56:59]
	v_mfma_f32_16x16x32_bf16 v[52:55], v[184:187], v[192:195], v[52:55]
	v_mfma_f32_16x16x32_bf16 v[52:55], v[188:191], v[196:199], v[52:55]
	v_mfma_f32_16x16x32_bf16 v[40:43], v[176:179], v[200:203], v[40:43]
	v_mfma_f32_16x16x32_bf16 v[40:43], v[180:183], v[204:207], v[40:43]
	v_mfma_f32_16x16x32_bf16 v[36:39], v[184:187], v[200:203], v[36:39]
	v_mfma_f32_16x16x32_bf16 v[36:39], v[188:191], v[204:207], v[36:39]
	v_mfma_f32_16x16x32_bf16 v[24:27], v[176:179], v[208:211], v[24:27]
	v_mfma_f32_16x16x32_bf16 v[24:27], v[180:183], v[212:215], v[24:27]
	v_mfma_f32_16x16x32_bf16 v[20:23], v[184:187], v[208:211], v[20:23]
	v_mfma_f32_16x16x32_bf16 v[20:23], v[188:191], v[212:215], v[20:23]
	v_mfma_f32_16x16x32_bf16 v[8:11], v[176:179], v[216:219], v[8:11]
	v_mfma_f32_16x16x32_bf16 v[8:11], v[180:183], v[220:223], v[8:11]
	v_mfma_f32_16x16x32_bf16 v[0:3], v[184:187], v[216:219], v[0:3]
	v_mfma_f32_16x16x32_bf16 v[0:3], v[188:191], v[220:223], v[0:3]
	s_barrier
	s_setprio 0
	s_add_i32 s70, s70, 2
	s_add_u32 s68, s68, 0x100
	s_addc_u32 s69, s69, 0
	s_add_u32 s40, s40, 0x100
	s_addc_u32 s41, s41, 0
	s_cmp_gt_u32 s70, 13
	s_cbranch_scc0 .LBB0_692
	s_and_b64 vcc, exec, s[16:17]
	s_cbranch_vccz .LBB0_695
	s_barrier
